# ROUTE epilogue (in-proj and LoRA GEMMs) rewritten by hand: wave owns 64 contiguous columns (B-fragment LDS addressing remapped), even/odd lane exchange so every store writes full 128-byte lines
# speedup vs baseline: 1.0572x; 1.0170x over previous
.LBB0_121:
	s_add_i32 m0, s3, 0x18000
	v_lshl_add_u64 v[10:11], v[10:11], 0, s[4:5]
	s_waitcnt vmcnt(2)
	s_barrier
	global_load_lds_dwordx4 v[10:11], off
	v_lshl_add_u64 v[6:7], v[6:7], 0, s[4:5]
	s_add_i32 m0, s3, 0x1a000
	s_add_i32 s80, s3, 0x8000
	global_load_lds_dwordx4 v[6:7], off
	v_lshl_add_u64 v[6:7], v[8:9], 0, s[4:5]
	s_mov_b32 m0, s80
	s_add_i32 s84, s3, 0xa000
	global_load_lds_dwordx4 v[6:7], off
	v_lshl_add_u64 v[6:7], v[12:13], 0, s[4:5]
	s_mov_b32 m0, s84
	v_lshl_add_u64 v[4:5], v[4:5], 0, s[4:5]
	global_load_lds_dwordx4 v[6:7], off
	s_add_i32 m0, s3, 0x1c000
	v_lshl_add_u64 v[2:3], v[2:3], 0, s[4:5]
	global_load_lds_dwordx4 v[4:5], off
	s_add_i32 m0, s3, 0x1e000
	s_lshl_b32 s11, s11, 5
	global_load_lds_dwordx4 v[2:3], off
	v_lshrrev_b32_e32 v2, 1, v15
	v_and_b32_e32 v2, 24, v2
	s_and_b32 s34, s11, 0x60
	v_and_b32_e32 v1, 15, v15
	v_lshlrev_b32_e32 v3, 1, v2
	v_or_b32_e32 v172, s34, v2
	v_rcp_iflag_f32_e32 v2, v14
	v_lshlrev_b32_e32 v241, 2, v1
	s_lshr_b32 s83, s10, 6
	v_lshl_or_b32 v3, v1, 6, v3
	v_and_b32_e32 v4, 32, v241
	s_mov_b32 s100, 0x14000
	s_mov_b32 s101, 0x1c000
	s_mov_b32 s11, 7
	s_cmp_eq_u32 s81, 0
	s_cbranch_scc1 .Lfl_remap
	s_branch .Lfl_noremap
.Lfl_remap:
	s_mov_b32 s100, 0x11000
	s_mov_b32 s101, 0x19000
	s_mov_b32 s11, 8
.Lfl_noremap:
	s_lshl_b32 s11, s34, s11
	s_lshl_b32 s10, s76, 6
	s_lshl_b32 s30, s76, 13
	v_bitop3_b32 v242, v3, s11, v4 bitop3:0xde
	s_add_i32 s11, s83, -2
	s_cmpk_lt_u32 s25, 0x100
	v_mul_f32_e32 v2, 0x4f7ffffe, v2
	v_bitop3_b32 v5, v3, s30, v4 bitop3:0xde
	s_cselect_b64 s[30:31], -1, 0
	s_ashr_i32 s59, s91, 31
	s_lshr_b32 s46, s24, 3
	v_cvt_u32_f32_e32 v2, v2
	s_waitcnt lgkmcnt(0)
	s_add_u32 s34, s48, 0x5800
	s_addc_u32 s35, s49, 0
	s_add_u32 s36, s48, 0xb000
	s_addc_u32 s37, s49, 0
	s_sub_i32 s42, 0, s90
	v_readfirstlane_b32 s43, v2
	s_waitcnt vmcnt(6)
	s_mul_i32 s42, s42, s43
	v_cmp_eq_u32_e64 s[40:41], 0, v1
	s_mul_hi_u32 s42, s43, s42
	s_mov_b32 s58, 0
	v_cndmask_b32_e64 v174, 2, 0, s[40:41]
	s_mov_b32 s25, s97
	s_add_i32 s47, s43, s42
	v_lshl_add_u64 v[176:177], s[96:97], 0, v[164:165]
	v_lshl_add_u64 v[178:179], s[96:97], 0, v[168:169]
	v_add_u32_e32 v243, 0, v5
	s_barrier
	s_branch .LBB0_124

.LBB0_131:
	s_add_i32 s74, s44, 2
	s_add_u32 s75, s38, 0x80
	s_addc_u32 s45, s39, 0
	s_add_i32 s94, 0, 0x10000
	s_cmp_eq_u32 s11, s44
	s_cselect_b32 s45, s93, s45
	s_cselect_b32 s44, s92, s75
	s_cselect_b32 s89, s99, s57
	s_cselect_b32 s88, s98, s56
	s_add_i32 s75, 0, 0x14000
	v_add_u32_e32 v142, s94, v242
	v_add_u32_e32 v158, s100, v242
	ds_read_b128 v[130:133], v142
	ds_read_b128 v[134:137], v142 offset:1024
	ds_read_b128 v[138:141], v142 offset:2048
	ds_read_b128 v[142:145], v142 offset:3072
	ds_read_b128 v[146:149], v158
	ds_read_b128 v[150:153], v158 offset:1024
	ds_read_b128 v[154:157], v158 offset:2048
	ds_read_b128 v[158:161], v158 offset:3072
	v_lshl_add_u64 v[212:213], s[38:39], 0, v[176:177]
	s_add_i32 m0, s3, 0xc000
	ds_read_b128 v[180:183], v243
	ds_read_b128 v[184:187], v243 offset:1024
	ds_read_b128 v[188:191], v243 offset:2048
	ds_read_b128 v[192:195], v243 offset:3072
	ds_read_b128 v[196:199], v243 offset:4096
	ds_read_b128 v[200:203], v243 offset:5120
	ds_read_b128 v[204:207], v243 offset:6144
	ds_read_b128 v[208:211], v243 offset:7168
	global_load_lds_dwordx4 v[212:213], off
	v_lshl_add_u64 v[212:213], s[38:39], 0, v[178:179]
	s_add_i32 m0, s3, 0xe000
	s_nop 0
	global_load_lds_dwordx4 v[212:213], off
	s_waitcnt vmcnt(8)
	s_waitcnt lgkmcnt(0)
	s_barrier
	s_setprio 1
	s_waitcnt lgkmcnt(0)
	v_mfma_f32_16x16x32_bf16 v[126:129], v[130:133], v[180:183], v[126:129]
	v_mfma_f32_16x16x32_bf16 v[122:125], v[138:141], v[180:183], v[122:125]
	v_mfma_f32_16x16x32_bf16 v[110:113], v[130:133], v[188:191], v[110:113]
	v_mfma_f32_16x16x32_bf16 v[106:109], v[138:141], v[188:191], v[106:109]
	v_mfma_f32_16x16x32_bf16 v[94:97], v[130:133], v[196:199], v[94:97]
	v_mfma_f32_16x16x32_bf16 v[90:93], v[138:141], v[196:199], v[90:93]
	v_mfma_f32_16x16x32_bf16 v[78:81], v[130:133], v[204:207], v[78:81]
	v_mfma_f32_16x16x32_bf16 v[74:77], v[138:141], v[204:207], v[74:77]
	v_mfma_f32_16x16x32_bf16 v[126:129], v[134:137], v[184:187], v[126:129]
	v_mfma_f32_16x16x32_bf16 v[122:125], v[142:145], v[184:187], v[122:125]
	v_mfma_f32_16x16x32_bf16 v[110:113], v[134:137], v[192:195], v[110:113]
	v_mfma_f32_16x16x32_bf16 v[106:109], v[142:145], v[192:195], v[106:109]
	v_mfma_f32_16x16x32_bf16 v[94:97], v[134:137], v[200:203], v[94:97]
	v_mfma_f32_16x16x32_bf16 v[90:93], v[142:145], v[200:203], v[90:93]
	v_mfma_f32_16x16x32_bf16 v[78:81], v[134:137], v[208:211], v[78:81]
	v_mfma_f32_16x16x32_bf16 v[74:77], v[142:145], v[208:211], v[74:77]
	s_setprio 0
	s_setprio 1
	v_mfma_f32_16x16x32_bf16 v[118:121], v[146:149], v[180:183], v[118:121]
	v_mfma_f32_16x16x32_bf16 v[114:117], v[154:157], v[180:183], v[114:117]
	v_mfma_f32_16x16x32_bf16 v[102:105], v[146:149], v[188:191], v[102:105]
	v_mfma_f32_16x16x32_bf16 v[98:101], v[154:157], v[188:191], v[98:101]
	v_mfma_f32_16x16x32_bf16 v[86:89], v[146:149], v[196:199], v[86:89]
	v_mfma_f32_16x16x32_bf16 v[82:85], v[154:157], v[196:199], v[82:85]
	v_mfma_f32_16x16x32_bf16 v[70:73], v[146:149], v[204:207], v[70:73]
	v_mfma_f32_16x16x32_bf16 v[66:69], v[154:157], v[204:207], v[66:69]
	v_mfma_f32_16x16x32_bf16 v[118:121], v[150:153], v[184:187], v[118:121]
	v_mfma_f32_16x16x32_bf16 v[114:117], v[158:161], v[184:187], v[114:117]
	v_mfma_f32_16x16x32_bf16 v[102:105], v[150:153], v[192:195], v[102:105]
	v_mfma_f32_16x16x32_bf16 v[98:101], v[158:161], v[192:195], v[98:101]
	v_mfma_f32_16x16x32_bf16 v[86:89], v[150:153], v[200:203], v[86:89]
	v_mfma_f32_16x16x32_bf16 v[82:85], v[158:161], v[200:203], v[82:85]
	v_mfma_f32_16x16x32_bf16 v[70:73], v[150:153], v[208:211], v[70:73]
	v_mfma_f32_16x16x32_bf16 v[66:69], v[158:161], v[208:211], v[66:69]
	s_setprio 0
	s_barrier
	s_add_i32 s94, s94, s77
	v_lshl_add_u64 v[212:213], s[88:89], 0, v[166:167]
	s_mov_b32 m0, s94
	ds_read_b128 v[180:183], v243 offset:16384
	ds_read_b128 v[184:187], v243 offset:17408
	ds_read_b128 v[188:191], v243 offset:18432
	ds_read_b128 v[192:195], v243 offset:19456
	ds_read_b128 v[196:199], v243 offset:20480
	ds_read_b128 v[200:203], v243 offset:21504
	ds_read_b128 v[204:207], v243 offset:22528
	ds_read_b128 v[208:211], v243 offset:23552
	global_load_lds_dwordx4 v[212:213], off
	s_add_i32 m0, s94, 0x2000
	v_lshl_add_u64 v[214:215], s[88:89], 0, v[170:171]
	s_add_u32 s88, s88, s96
	s_addc_u32 s89, s89, 0
	s_add_i32 s75, s75, s77
	global_load_lds_dwordx4 v[214:215], off
	v_lshl_add_u64 v[216:217], s[88:89], 0, v[166:167]
	s_mov_b32 m0, s75
	v_lshl_add_u64 v[218:219], s[88:89], 0, v[170:171]
	global_load_lds_dwordx4 v[216:217], off
	s_add_i32 m0, s75, 0x2000
	v_lshl_add_u64 v[220:221], s[44:45], 0, v[164:165]
	global_load_lds_dwordx4 v[218:219], off
	s_mov_b32 m0, s3
	v_lshl_add_u64 v[222:223], s[44:45], 0, v[168:169]
	global_load_lds_dwordx4 v[220:221], off
	s_mov_b32 m0, s78
	s_nop 0
	global_load_lds_dwordx4 v[222:223], off
	s_waitcnt vmcnt(8)
	s_waitcnt lgkmcnt(0)
	s_barrier
	s_setprio 1
	s_waitcnt lgkmcnt(0)
	v_mfma_f32_16x16x32_bf16 v[62:65], v[130:133], v[180:183], v[62:65]
	v_mfma_f32_16x16x32_bf16 v[58:61], v[138:141], v[180:183], v[58:61]
	v_mfma_f32_16x16x32_bf16 v[46:49], v[130:133], v[188:191], v[46:49]
	v_mfma_f32_16x16x32_bf16 v[42:45], v[138:141], v[188:191], v[42:45]
	v_mfma_f32_16x16x32_bf16 v[30:33], v[130:133], v[196:199], v[30:33]
	v_mfma_f32_16x16x32_bf16 v[26:29], v[138:141], v[196:199], v[26:29]
	v_mfma_f32_16x16x32_bf16 v[14:17], v[130:133], v[204:207], v[14:17]
	v_mfma_f32_16x16x32_bf16 v[10:13], v[138:141], v[204:207], v[10:13]
	v_mfma_f32_16x16x32_bf16 v[62:65], v[134:137], v[184:187], v[62:65]
	v_mfma_f32_16x16x32_bf16 v[58:61], v[142:145], v[184:187], v[58:61]
	v_mfma_f32_16x16x32_bf16 v[46:49], v[134:137], v[192:195], v[46:49]
	v_mfma_f32_16x16x32_bf16 v[42:45], v[142:145], v[192:195], v[42:45]
	v_mfma_f32_16x16x32_bf16 v[30:33], v[134:137], v[200:203], v[30:33]
	v_mfma_f32_16x16x32_bf16 v[26:29], v[142:145], v[200:203], v[26:29]
	v_mfma_f32_16x16x32_bf16 v[14:17], v[134:137], v[208:211], v[14:17]
	v_mfma_f32_16x16x32_bf16 v[10:13], v[142:145], v[208:211], v[10:13]
	s_setprio 0
	s_setprio 1
	v_mfma_f32_16x16x32_bf16 v[54:57], v[146:149], v[180:183], v[54:57]
	v_mfma_f32_16x16x32_bf16 v[50:53], v[154:157], v[180:183], v[50:53]
	v_mfma_f32_16x16x32_bf16 v[38:41], v[146:149], v[188:191], v[38:41]
	v_mfma_f32_16x16x32_bf16 v[34:37], v[154:157], v[188:191], v[34:37]
	v_mfma_f32_16x16x32_bf16 v[22:25], v[146:149], v[196:199], v[22:25]
	v_mfma_f32_16x16x32_bf16 v[18:21], v[154:157], v[196:199], v[18:21]
	v_mfma_f32_16x16x32_bf16 v[6:9], v[146:149], v[204:207], v[6:9]
	v_mfma_f32_16x16x32_bf16 v[2:5], v[154:157], v[204:207], v[2:5]
	v_mfma_f32_16x16x32_bf16 v[54:57], v[150:153], v[184:187], v[54:57]
	v_mfma_f32_16x16x32_bf16 v[50:53], v[158:161], v[184:187], v[50:53]
	v_mfma_f32_16x16x32_bf16 v[38:41], v[150:153], v[192:195], v[38:41]
	v_mfma_f32_16x16x32_bf16 v[34:37], v[158:161], v[192:195], v[34:37]
	v_mfma_f32_16x16x32_bf16 v[22:25], v[150:153], v[200:203], v[22:25]
	v_mfma_f32_16x16x32_bf16 v[18:21], v[158:161], v[200:203], v[18:21]
	v_mfma_f32_16x16x32_bf16 v[6:9], v[150:153], v[208:211], v[6:9]
	v_mfma_f32_16x16x32_bf16 v[2:5], v[158:161], v[208:211], v[2:5]
	s_setprio 0
	s_barrier
	s_add_i32 s75, 0, 0x18000
	s_add_i32 s88, 0, 0x1c000
	v_add_u32_e32 v142, s75, v242
	v_add_u32_e32 v158, s101, v242
	ds_read_b128 v[130:133], v142
	ds_read_b128 v[134:137], v142 offset:1024
	ds_read_b128 v[138:141], v142 offset:2048
	ds_read_b128 v[142:145], v142 offset:3072
	ds_read_b128 v[146:149], v158
	ds_read_b128 v[150:153], v158 offset:1024
	ds_read_b128 v[154:157], v158 offset:2048
	ds_read_b128 v[158:161], v158 offset:3072
	s_add_u32 s44, s44, s96
	s_addc_u32 s45, s45, 0
	s_mov_b32 m0, s9
	v_lshl_add_u64 v[224:225], s[44:45], 0, v[164:165]
	ds_read_b128 v[180:183], v243 offset:32768
	ds_read_b128 v[184:187], v243 offset:33792
	ds_read_b128 v[188:191], v243 offset:34816
	ds_read_b128 v[192:195], v243 offset:35840
	ds_read_b128 v[196:199], v243 offset:36864
	ds_read_b128 v[200:203], v243 offset:37888
	ds_read_b128 v[204:207], v243 offset:38912
	ds_read_b128 v[208:211], v243 offset:39936
	global_load_lds_dwordx4 v[224:225], off
	v_lshl_add_u64 v[224:225], s[44:45], 0, v[168:169]
	s_mov_b32 m0, s86
	s_nop 0
	global_load_lds_dwordx4 v[224:225], off
	s_waitcnt vmcnt(8)
	s_waitcnt lgkmcnt(0)
	s_barrier
	s_setprio 1
	s_waitcnt lgkmcnt(0)
	v_mfma_f32_16x16x32_bf16 v[126:129], v[130:133], v[180:183], v[126:129]
	v_mfma_f32_16x16x32_bf16 v[122:125], v[138:141], v[180:183], v[122:125]
	v_mfma_f32_16x16x32_bf16 v[110:113], v[130:133], v[188:191], v[110:113]
	v_mfma_f32_16x16x32_bf16 v[106:109], v[138:141], v[188:191], v[106:109]
	v_mfma_f32_16x16x32_bf16 v[94:97], v[130:133], v[196:199], v[94:97]
	v_mfma_f32_16x16x32_bf16 v[90:93], v[138:141], v[196:199], v[90:93]
	v_mfma_f32_16x16x32_bf16 v[78:81], v[130:133], v[204:207], v[78:81]
	v_mfma_f32_16x16x32_bf16 v[74:77], v[138:141], v[204:207], v[74:77]
	v_mfma_f32_16x16x32_bf16 v[126:129], v[134:137], v[184:187], v[126:129]
	v_mfma_f32_16x16x32_bf16 v[122:125], v[142:145], v[184:187], v[122:125]
	v_mfma_f32_16x16x32_bf16 v[110:113], v[134:137], v[192:195], v[110:113]
	v_mfma_f32_16x16x32_bf16 v[106:109], v[142:145], v[192:195], v[106:109]
	v_mfma_f32_16x16x32_bf16 v[94:97], v[134:137], v[200:203], v[94:97]
	v_mfma_f32_16x16x32_bf16 v[90:93], v[142:145], v[200:203], v[90:93]
	v_mfma_f32_16x16x32_bf16 v[78:81], v[134:137], v[208:211], v[78:81]
	v_mfma_f32_16x16x32_bf16 v[74:77], v[142:145], v[208:211], v[74:77]
	s_setprio 0
	s_setprio 1
	v_mfma_f32_16x16x32_bf16 v[118:121], v[146:149], v[180:183], v[118:121]
	v_mfma_f32_16x16x32_bf16 v[114:117], v[154:157], v[180:183], v[114:117]
	v_mfma_f32_16x16x32_bf16 v[102:105], v[146:149], v[188:191], v[102:105]
	v_mfma_f32_16x16x32_bf16 v[98:101], v[154:157], v[188:191], v[98:101]
	v_mfma_f32_16x16x32_bf16 v[86:89], v[146:149], v[196:199], v[86:89]
	v_mfma_f32_16x16x32_bf16 v[82:85], v[154:157], v[196:199], v[82:85]
	v_mfma_f32_16x16x32_bf16 v[70:73], v[146:149], v[204:207], v[70:73]
	v_mfma_f32_16x16x32_bf16 v[66:69], v[154:157], v[204:207], v[66:69]
	v_mfma_f32_16x16x32_bf16 v[118:121], v[150:153], v[184:187], v[118:121]
	v_mfma_f32_16x16x32_bf16 v[114:117], v[158:161], v[184:187], v[114:117]
	v_mfma_f32_16x16x32_bf16 v[102:105], v[150:153], v[192:195], v[102:105]
	v_mfma_f32_16x16x32_bf16 v[98:101], v[158:161], v[192:195], v[98:101]
	v_mfma_f32_16x16x32_bf16 v[86:89], v[150:153], v[200:203], v[86:89]
	v_mfma_f32_16x16x32_bf16 v[82:85], v[158:161], v[200:203], v[82:85]
	v_mfma_f32_16x16x32_bf16 v[70:73], v[150:153], v[208:211], v[70:73]
	v_mfma_f32_16x16x32_bf16 v[66:69], v[158:161], v[208:211], v[66:69]
	s_setprio 0
	s_barrier
	s_add_i32 s44, s75, s77
	v_lshl_add_u64 v[212:213], v[212:213], 0, s[4:5]
	s_mov_b32 m0, s44
	ds_read_b128 v[180:183], v243 offset:49152
	ds_read_b128 v[184:187], v243 offset:50176
	ds_read_b128 v[188:191], v243 offset:51200
	ds_read_b128 v[192:195], v243 offset:52224
	ds_read_b128 v[196:199], v243 offset:53248
	ds_read_b128 v[200:203], v243 offset:54272
	ds_read_b128 v[204:207], v243 offset:55296
	ds_read_b128 v[208:211], v243 offset:56320
	global_load_lds_dwordx4 v[212:213], off
	v_lshl_add_u64 v[212:213], v[214:215], 0, s[4:5]
	s_add_i32 m0, s44, 0x2000
	s_add_i32 s44, s88, s77
	global_load_lds_dwordx4 v[212:213], off
	v_lshl_add_u64 v[212:213], v[216:217], 0, s[4:5]
	s_mov_b32 m0, s44
	s_nop 0
	global_load_lds_dwordx4 v[212:213], off
	v_lshl_add_u64 v[212:213], v[218:219], 0, s[4:5]
	s_add_i32 m0, s44, 0x2000
	s_nop 0
	global_load_lds_dwordx4 v[212:213], off
	v_lshl_add_u64 v[212:213], v[220:221], 0, s[4:5]
	s_mov_b32 m0, s80
	s_nop 0
	global_load_lds_dwordx4 v[212:213], off
	v_lshl_add_u64 v[212:213], v[222:223], 0, s[4:5]
	s_mov_b32 m0, s84
	s_nop 0
	global_load_lds_dwordx4 v[212:213], off
	s_waitcnt vmcnt(8)
	s_waitcnt lgkmcnt(0)
	s_barrier
	s_setprio 1
	s_waitcnt lgkmcnt(0)
	v_mfma_f32_16x16x32_bf16 v[62:65], v[130:133], v[180:183], v[62:65]
	v_mfma_f32_16x16x32_bf16 v[58:61], v[138:141], v[180:183], v[58:61]
	v_mfma_f32_16x16x32_bf16 v[46:49], v[130:133], v[188:191], v[46:49]
	v_mfma_f32_16x16x32_bf16 v[42:45], v[138:141], v[188:191], v[42:45]
	v_mfma_f32_16x16x32_bf16 v[30:33], v[130:133], v[196:199], v[30:33]
	v_mfma_f32_16x16x32_bf16 v[26:29], v[138:141], v[196:199], v[26:29]
	v_mfma_f32_16x16x32_bf16 v[14:17], v[130:133], v[204:207], v[14:17]
	v_mfma_f32_16x16x32_bf16 v[10:13], v[138:141], v[204:207], v[10:13]
	v_mfma_f32_16x16x32_bf16 v[62:65], v[134:137], v[184:187], v[62:65]
	v_mfma_f32_16x16x32_bf16 v[58:61], v[142:145], v[184:187], v[58:61]
	v_mfma_f32_16x16x32_bf16 v[46:49], v[134:137], v[192:195], v[46:49]
	v_mfma_f32_16x16x32_bf16 v[42:45], v[142:145], v[192:195], v[42:45]
	v_mfma_f32_16x16x32_bf16 v[30:33], v[134:137], v[200:203], v[30:33]
	v_mfma_f32_16x16x32_bf16 v[26:29], v[142:145], v[200:203], v[26:29]
	v_mfma_f32_16x16x32_bf16 v[14:17], v[134:137], v[208:211], v[14:17]
	v_mfma_f32_16x16x32_bf16 v[10:13], v[142:145], v[208:211], v[10:13]
	s_setprio 0
	s_setprio 1
	v_mfma_f32_16x16x32_bf16 v[54:57], v[146:149], v[180:183], v[54:57]
	v_mfma_f32_16x16x32_bf16 v[50:53], v[154:157], v[180:183], v[50:53]
	v_mfma_f32_16x16x32_bf16 v[38:41], v[146:149], v[188:191], v[38:41]
	v_mfma_f32_16x16x32_bf16 v[34:37], v[154:157], v[188:191], v[34:37]
	v_mfma_f32_16x16x32_bf16 v[22:25], v[146:149], v[196:199], v[22:25]
	v_mfma_f32_16x16x32_bf16 v[18:21], v[154:157], v[196:199], v[18:21]
	v_mfma_f32_16x16x32_bf16 v[6:9], v[146:149], v[204:207], v[6:9]
	v_mfma_f32_16x16x32_bf16 v[2:5], v[154:157], v[204:207], v[2:5]
	v_mfma_f32_16x16x32_bf16 v[54:57], v[150:153], v[184:187], v[54:57]
	v_mfma_f32_16x16x32_bf16 v[50:53], v[158:161], v[184:187], v[50:53]
	v_mfma_f32_16x16x32_bf16 v[38:41], v[150:153], v[192:195], v[38:41]
	v_mfma_f32_16x16x32_bf16 v[34:37], v[158:161], v[192:195], v[34:37]
	v_mfma_f32_16x16x32_bf16 v[22:25], v[150:153], v[200:203], v[22:25]
	v_mfma_f32_16x16x32_bf16 v[18:21], v[158:161], v[200:203], v[18:21]
	v_mfma_f32_16x16x32_bf16 v[6:9], v[150:153], v[208:211], v[6:9]
	v_mfma_f32_16x16x32_bf16 v[2:5], v[158:161], v[208:211], v[2:5]
	s_setprio 0
	s_barrier
	s_add_u32 s38, s38, 0x100
	s_addc_u32 s39, s39, 0
	s_add_u32 s56, s56, 0x100
	s_addc_u32 s57, s57, 0
	s_cmp_ge_u32 s74, s83
	s_mov_b32 s44, s74
	s_cbranch_scc0 .LBB0_131
	s_and_b64 vcc, exec, s[30:31]
	s_cbranch_vccz .LBB0_134
	s_barrier

.LBB0_187:
	s_mov_b32 s54, s44
	v_cndmask_b32_e64 v130, 0, 1, s[74:75]
	v_cmp_ne_u32_e64 s[44:45], 1, v130
	s_andn2_b64 vcc, exec, s[74:75]
	s_branch .Lroute_go
.LBB0_188:
	s_mov_b64 s[38:39], s[52:53]
	s_mov_b64 s[88:89], s[18:19]
	v_cndmask_b32_e64 v130, 0, 1, s[74:75]
	v_cmp_ne_u32_e64 s[44:45], 1, v130
	s_andn2_b64 vcc, exec, s[74:75]
	s_branch .Lroute_go
.Lroute_go:
	v_and_b32_e32 v130, 1, v180
	v_and_b32_e32 v131, -2, v180
	v_bfe_u32 v132, v163, 4, 2
	v_bfe_u32 v133, v163, 6, 2
	v_lshlrev_b32_e32 v132, 3, v132
	v_lshl_add_u32 v132, v133, 6, v132
	v_lshl_add_u32 v132, v130, 5, v132
	v_add_u32_e32 v132, s54, v132
	v_mul_lo_u32 v134, s38, v131
	v_add_u32_e32 v134, v134, v132
	v_mov_b32_e32 v135, 0
	v_lshl_add_u64 v[134:135], v[134:135], 1, s[88:89]
	s_lshl_b32 s56, s38, 1
	s_mov_b32 s57, 0
	s_lshl_b32 s44, s38, 5
	s_mov_b32 s45, 0
	s_mov_b32 vcc_lo, 0x55555555
	s_mov_b32 vcc_hi, 0x55555555
	s_cmp_lg_u32 s74, 0
	s_cbranch_scc0 .Lroute_ns0
	v_mul_f32_e32 v114, 0xbfb8aa3b, v114
	v_mul_f32_e32 v115, 0xbfb8aa3b, v115
	v_mul_f32_e32 v116, 0xbfb8aa3b, v116
	v_mul_f32_e32 v117, 0xbfb8aa3b, v117
	v_mul_f32_e32 v118, 0xbfb8aa3b, v118
	v_mul_f32_e32 v119, 0xbfb8aa3b, v119
	v_mul_f32_e32 v120, 0xbfb8aa3b, v120
	v_mul_f32_e32 v121, 0xbfb8aa3b, v121
	v_mul_f32_e32 v122, 0xbfb8aa3b, v122
	v_mul_f32_e32 v123, 0xbfb8aa3b, v123
	v_mul_f32_e32 v124, 0xbfb8aa3b, v124
	v_mul_f32_e32 v125, 0xbfb8aa3b, v125
	v_mul_f32_e32 v126, 0xbfb8aa3b, v126
	v_mul_f32_e32 v127, 0xbfb8aa3b, v127
	v_mul_f32_e32 v128, 0xbfb8aa3b, v128
	v_mul_f32_e32 v129, 0xbfb8aa3b, v129
	v_exp_f32_e32 v114, v114
	v_exp_f32_e32 v115, v115
	v_exp_f32_e32 v116, v116
	v_exp_f32_e32 v117, v117
	v_exp_f32_e32 v118, v118
	v_exp_f32_e32 v119, v119
	v_exp_f32_e32 v120, v120
	v_exp_f32_e32 v121, v121
	v_exp_f32_e32 v122, v122
	v_exp_f32_e32 v123, v123
	v_exp_f32_e32 v124, v124
	v_exp_f32_e32 v125, v125
	v_exp_f32_e32 v126, v126
	v_exp_f32_e32 v127, v127
	v_exp_f32_e32 v128, v128
	v_exp_f32_e32 v129, v129
	v_add_f32_e32 v114, 1.0, v114
	v_add_f32_e32 v115, 1.0, v115
	v_add_f32_e32 v116, 1.0, v116
	v_add_f32_e32 v117, 1.0, v117
	v_add_f32_e32 v118, 1.0, v118
	v_add_f32_e32 v119, 1.0, v119
	v_add_f32_e32 v120, 1.0, v120
	v_add_f32_e32 v121, 1.0, v121
	v_add_f32_e32 v122, 1.0, v122
	v_add_f32_e32 v123, 1.0, v123
	v_add_f32_e32 v124, 1.0, v124
	v_add_f32_e32 v125, 1.0, v125
	v_add_f32_e32 v126, 1.0, v126
	v_add_f32_e32 v127, 1.0, v127
	v_add_f32_e32 v128, 1.0, v128
	v_add_f32_e32 v129, 1.0, v129
	v_rcp_f32_e32 v114, v114
	v_rcp_f32_e32 v115, v115
	v_rcp_f32_e32 v116, v116
	v_rcp_f32_e32 v117, v117
	v_rcp_f32_e32 v118, v118
	v_rcp_f32_e32 v119, v119
	v_rcp_f32_e32 v120, v120
	v_rcp_f32_e32 v121, v121
	v_rcp_f32_e32 v122, v122
	v_rcp_f32_e32 v123, v123
	v_rcp_f32_e32 v124, v124
	v_rcp_f32_e32 v125, v125
	v_rcp_f32_e32 v126, v126
	v_rcp_f32_e32 v127, v127
	v_rcp_f32_e32 v128, v128
	v_rcp_f32_e32 v129, v129
	s_nop 0
.Lroute_ns0:
	v_cvt_pk_bf16_f32 v136, v126, v127
	v_cvt_pk_bf16_f32 v137, v128, v129
	v_cvt_pk_bf16_f32 v138, v122, v123
	v_cvt_pk_bf16_f32 v139, v124, v125
	v_cvt_pk_bf16_f32 v140, v118, v119
	v_cvt_pk_bf16_f32 v141, v120, v121
	v_cvt_pk_bf16_f32 v142, v114, v115
	v_cvt_pk_bf16_f32 v143, v116, v117
	v_lshl_add_u64 v[152:153], s[56:57], 0, v[134:135]
	v_cndmask_b32_dpp v144, v140, v136, vcc quad_perm:[1,0,3,2] row_mask:0xf bank_mask:0xf
	v_cndmask_b32_dpp v145, v141, v137, vcc quad_perm:[1,0,3,2] row_mask:0xf bank_mask:0xf
	v_cndmask_b32_dpp v146, v142, v138, vcc quad_perm:[1,0,3,2] row_mask:0xf bank_mask:0xf
	v_cndmask_b32_dpp v147, v143, v139, vcc quad_perm:[1,0,3,2] row_mask:0xf bank_mask:0xf
	s_not_b64 vcc, vcc
	global_store_dwordx4 v[134:135], v[144:147], off nt
	s_nop 0
	v_cndmask_b32_dpp v148, v136, v140, vcc quad_perm:[1,0,3,2] row_mask:0xf bank_mask:0xf
	v_cndmask_b32_dpp v149, v137, v141, vcc quad_perm:[1,0,3,2] row_mask:0xf bank_mask:0xf
	v_cndmask_b32_dpp v150, v138, v142, vcc quad_perm:[1,0,3,2] row_mask:0xf bank_mask:0xf
	v_cndmask_b32_dpp v151, v139, v143, vcc quad_perm:[1,0,3,2] row_mask:0xf bank_mask:0xf
	s_not_b64 vcc, vcc
	global_store_dwordx4 v[152:153], v[148:151], off nt
	v_lshl_add_u64 v[134:135], s[44:45], 0, v[134:135]
	s_cmp_lg_u32 s74, 0
	s_cbranch_scc0 .Lroute_ns1
	v_mul_f32_e32 v98, 0xbfb8aa3b, v98
	v_mul_f32_e32 v99, 0xbfb8aa3b, v99
	v_mul_f32_e32 v100, 0xbfb8aa3b, v100
	v_mul_f32_e32 v101, 0xbfb8aa3b, v101
	v_mul_f32_e32 v102, 0xbfb8aa3b, v102
	v_mul_f32_e32 v103, 0xbfb8aa3b, v103
	v_mul_f32_e32 v104, 0xbfb8aa3b, v104
	v_mul_f32_e32 v105, 0xbfb8aa3b, v105
	v_mul_f32_e32 v106, 0xbfb8aa3b, v106
	v_mul_f32_e32 v107, 0xbfb8aa3b, v107
	v_mul_f32_e32 v108, 0xbfb8aa3b, v108
	v_mul_f32_e32 v109, 0xbfb8aa3b, v109
	v_mul_f32_e32 v110, 0xbfb8aa3b, v110
	v_mul_f32_e32 v111, 0xbfb8aa3b, v111
	v_mul_f32_e32 v112, 0xbfb8aa3b, v112
	v_mul_f32_e32 v113, 0xbfb8aa3b, v113
	v_exp_f32_e32 v98, v98
	v_exp_f32_e32 v99, v99
	v_exp_f32_e32 v100, v100
	v_exp_f32_e32 v101, v101
	v_exp_f32_e32 v102, v102
	v_exp_f32_e32 v103, v103
	v_exp_f32_e32 v104, v104
	v_exp_f32_e32 v105, v105
	v_exp_f32_e32 v106, v106
	v_exp_f32_e32 v107, v107
	v_exp_f32_e32 v108, v108
	v_exp_f32_e32 v109, v109
	v_exp_f32_e32 v110, v110
	v_exp_f32_e32 v111, v111
	v_exp_f32_e32 v112, v112
	v_exp_f32_e32 v113, v113
	v_add_f32_e32 v98, 1.0, v98
	v_add_f32_e32 v99, 1.0, v99
	v_add_f32_e32 v100, 1.0, v100
	v_add_f32_e32 v101, 1.0, v101
	v_add_f32_e32 v102, 1.0, v102
	v_add_f32_e32 v103, 1.0, v103
	v_add_f32_e32 v104, 1.0, v104
	v_add_f32_e32 v105, 1.0, v105
	v_add_f32_e32 v106, 1.0, v106
	v_add_f32_e32 v107, 1.0, v107
	v_add_f32_e32 v108, 1.0, v108
	v_add_f32_e32 v109, 1.0, v109
	v_add_f32_e32 v110, 1.0, v110
	v_add_f32_e32 v111, 1.0, v111
	v_add_f32_e32 v112, 1.0, v112
	v_add_f32_e32 v113, 1.0, v113
	v_rcp_f32_e32 v98, v98
	v_rcp_f32_e32 v99, v99
	v_rcp_f32_e32 v100, v100
	v_rcp_f32_e32 v101, v101
	v_rcp_f32_e32 v102, v102
	v_rcp_f32_e32 v103, v103
	v_rcp_f32_e32 v104, v104
	v_rcp_f32_e32 v105, v105
	v_rcp_f32_e32 v106, v106
	v_rcp_f32_e32 v107, v107
	v_rcp_f32_e32 v108, v108
	v_rcp_f32_e32 v109, v109
	v_rcp_f32_e32 v110, v110
	v_rcp_f32_e32 v111, v111
	v_rcp_f32_e32 v112, v112
	v_rcp_f32_e32 v113, v113
	s_nop 0
.Lroute_ns1:
	v_cvt_pk_bf16_f32 v154, v110, v111
	v_cvt_pk_bf16_f32 v155, v112, v113
	v_cvt_pk_bf16_f32 v156, v106, v107
	v_cvt_pk_bf16_f32 v157, v108, v109
	v_cvt_pk_bf16_f32 v158, v102, v103
	v_cvt_pk_bf16_f32 v159, v104, v105
	v_cvt_pk_bf16_f32 v160, v98, v99
	v_cvt_pk_bf16_f32 v161, v100, v101
	v_lshl_add_u64 v[152:153], s[56:57], 0, v[134:135]
	v_cndmask_b32_dpp v212, v158, v154, vcc quad_perm:[1,0,3,2] row_mask:0xf bank_mask:0xf
	v_cndmask_b32_dpp v213, v159, v155, vcc quad_perm:[1,0,3,2] row_mask:0xf bank_mask:0xf
	v_cndmask_b32_dpp v214, v160, v156, vcc quad_perm:[1,0,3,2] row_mask:0xf bank_mask:0xf
	v_cndmask_b32_dpp v215, v161, v157, vcc quad_perm:[1,0,3,2] row_mask:0xf bank_mask:0xf
	s_not_b64 vcc, vcc
	global_store_dwordx4 v[134:135], v[212:215], off nt
	s_nop 0
	v_cndmask_b32_dpp v216, v154, v158, vcc quad_perm:[1,0,3,2] row_mask:0xf bank_mask:0xf
	v_cndmask_b32_dpp v217, v155, v159, vcc quad_perm:[1,0,3,2] row_mask:0xf bank_mask:0xf
	v_cndmask_b32_dpp v218, v156, v160, vcc quad_perm:[1,0,3,2] row_mask:0xf bank_mask:0xf
	v_cndmask_b32_dpp v219, v157, v161, vcc quad_perm:[1,0,3,2] row_mask:0xf bank_mask:0xf
	s_not_b64 vcc, vcc
	global_store_dwordx4 v[152:153], v[216:219], off nt
	v_lshl_add_u64 v[134:135], s[44:45], 0, v[134:135]
	s_cmp_lg_u32 s74, 0
	s_cbranch_scc0 .Lroute_ns2
	v_mul_f32_e32 v82, 0xbfb8aa3b, v82
	v_mul_f32_e32 v83, 0xbfb8aa3b, v83
	v_mul_f32_e32 v84, 0xbfb8aa3b, v84
	v_mul_f32_e32 v85, 0xbfb8aa3b, v85
	v_mul_f32_e32 v86, 0xbfb8aa3b, v86
	v_mul_f32_e32 v87, 0xbfb8aa3b, v87
	v_mul_f32_e32 v88, 0xbfb8aa3b, v88
	v_mul_f32_e32 v89, 0xbfb8aa3b, v89
	v_mul_f32_e32 v90, 0xbfb8aa3b, v90
	v_mul_f32_e32 v91, 0xbfb8aa3b, v91
	v_mul_f32_e32 v92, 0xbfb8aa3b, v92
	v_mul_f32_e32 v93, 0xbfb8aa3b, v93
	v_mul_f32_e32 v94, 0xbfb8aa3b, v94
	v_mul_f32_e32 v95, 0xbfb8aa3b, v95
	v_mul_f32_e32 v96, 0xbfb8aa3b, v96
	v_mul_f32_e32 v97, 0xbfb8aa3b, v97
	v_exp_f32_e32 v82, v82
	v_exp_f32_e32 v83, v83
	v_exp_f32_e32 v84, v84
	v_exp_f32_e32 v85, v85
	v_exp_f32_e32 v86, v86
	v_exp_f32_e32 v87, v87
	v_exp_f32_e32 v88, v88
	v_exp_f32_e32 v89, v89
	v_exp_f32_e32 v90, v90
	v_exp_f32_e32 v91, v91
	v_exp_f32_e32 v92, v92
	v_exp_f32_e32 v93, v93
	v_exp_f32_e32 v94, v94
	v_exp_f32_e32 v95, v95
	v_exp_f32_e32 v96, v96
	v_exp_f32_e32 v97, v97
	v_add_f32_e32 v82, 1.0, v82
	v_add_f32_e32 v83, 1.0, v83
	v_add_f32_e32 v84, 1.0, v84
	v_add_f32_e32 v85, 1.0, v85
	v_add_f32_e32 v86, 1.0, v86
	v_add_f32_e32 v87, 1.0, v87
	v_add_f32_e32 v88, 1.0, v88
	v_add_f32_e32 v89, 1.0, v89
	v_add_f32_e32 v90, 1.0, v90
	v_add_f32_e32 v91, 1.0, v91
	v_add_f32_e32 v92, 1.0, v92
	v_add_f32_e32 v93, 1.0, v93
	v_add_f32_e32 v94, 1.0, v94
	v_add_f32_e32 v95, 1.0, v95
	v_add_f32_e32 v96, 1.0, v96
	v_add_f32_e32 v97, 1.0, v97
	v_rcp_f32_e32 v82, v82
	v_rcp_f32_e32 v83, v83
	v_rcp_f32_e32 v84, v84
	v_rcp_f32_e32 v85, v85
	v_rcp_f32_e32 v86, v86
	v_rcp_f32_e32 v87, v87
	v_rcp_f32_e32 v88, v88
	v_rcp_f32_e32 v89, v89
	v_rcp_f32_e32 v90, v90
	v_rcp_f32_e32 v91, v91
	v_rcp_f32_e32 v92, v92
	v_rcp_f32_e32 v93, v93
	v_rcp_f32_e32 v94, v94
	v_rcp_f32_e32 v95, v95
	v_rcp_f32_e32 v96, v96
	v_rcp_f32_e32 v97, v97
	s_nop 0
.Lroute_ns2:
	v_cvt_pk_bf16_f32 v136, v94, v95
	v_cvt_pk_bf16_f32 v137, v96, v97
	v_cvt_pk_bf16_f32 v138, v90, v91
	v_cvt_pk_bf16_f32 v139, v92, v93
	v_cvt_pk_bf16_f32 v140, v86, v87
	v_cvt_pk_bf16_f32 v141, v88, v89
	v_cvt_pk_bf16_f32 v142, v82, v83
	v_cvt_pk_bf16_f32 v143, v84, v85
	v_lshl_add_u64 v[152:153], s[56:57], 0, v[134:135]
	v_cndmask_b32_dpp v144, v140, v136, vcc quad_perm:[1,0,3,2] row_mask:0xf bank_mask:0xf
	v_cndmask_b32_dpp v145, v141, v137, vcc quad_perm:[1,0,3,2] row_mask:0xf bank_mask:0xf
	v_cndmask_b32_dpp v146, v142, v138, vcc quad_perm:[1,0,3,2] row_mask:0xf bank_mask:0xf
	v_cndmask_b32_dpp v147, v143, v139, vcc quad_perm:[1,0,3,2] row_mask:0xf bank_mask:0xf
	s_not_b64 vcc, vcc
	global_store_dwordx4 v[134:135], v[144:147], off nt
	s_nop 0
	v_cndmask_b32_dpp v148, v136, v140, vcc quad_perm:[1,0,3,2] row_mask:0xf bank_mask:0xf
	v_cndmask_b32_dpp v149, v137, v141, vcc quad_perm:[1,0,3,2] row_mask:0xf bank_mask:0xf
	v_cndmask_b32_dpp v150, v138, v142, vcc quad_perm:[1,0,3,2] row_mask:0xf bank_mask:0xf
	v_cndmask_b32_dpp v151, v139, v143, vcc quad_perm:[1,0,3,2] row_mask:0xf bank_mask:0xf
	s_not_b64 vcc, vcc
	global_store_dwordx4 v[152:153], v[148:151], off nt
	v_lshl_add_u64 v[134:135], s[44:45], 0, v[134:135]
	s_cmp_lg_u32 s74, 0
	s_cbranch_scc0 .Lroute_ns3
	v_mul_f32_e32 v66, 0xbfb8aa3b, v66
	v_mul_f32_e32 v67, 0xbfb8aa3b, v67
	v_mul_f32_e32 v68, 0xbfb8aa3b, v68
	v_mul_f32_e32 v69, 0xbfb8aa3b, v69
	v_mul_f32_e32 v70, 0xbfb8aa3b, v70
	v_mul_f32_e32 v71, 0xbfb8aa3b, v71
	v_mul_f32_e32 v72, 0xbfb8aa3b, v72
	v_mul_f32_e32 v73, 0xbfb8aa3b, v73
	v_mul_f32_e32 v74, 0xbfb8aa3b, v74
	v_mul_f32_e32 v75, 0xbfb8aa3b, v75
	v_mul_f32_e32 v76, 0xbfb8aa3b, v76
	v_mul_f32_e32 v77, 0xbfb8aa3b, v77
	v_mul_f32_e32 v78, 0xbfb8aa3b, v78
	v_mul_f32_e32 v79, 0xbfb8aa3b, v79
	v_mul_f32_e32 v80, 0xbfb8aa3b, v80
	v_mul_f32_e32 v81, 0xbfb8aa3b, v81
	v_exp_f32_e32 v66, v66
	v_exp_f32_e32 v67, v67
	v_exp_f32_e32 v68, v68
	v_exp_f32_e32 v69, v69
	v_exp_f32_e32 v70, v70
	v_exp_f32_e32 v71, v71
	v_exp_f32_e32 v72, v72
	v_exp_f32_e32 v73, v73
	v_exp_f32_e32 v74, v74
	v_exp_f32_e32 v75, v75
	v_exp_f32_e32 v76, v76
	v_exp_f32_e32 v77, v77
	v_exp_f32_e32 v78, v78
	v_exp_f32_e32 v79, v79
	v_exp_f32_e32 v80, v80
	v_exp_f32_e32 v81, v81
	v_add_f32_e32 v66, 1.0, v66
	v_add_f32_e32 v67, 1.0, v67
	v_add_f32_e32 v68, 1.0, v68
	v_add_f32_e32 v69, 1.0, v69
	v_add_f32_e32 v70, 1.0, v70
	v_add_f32_e32 v71, 1.0, v71
	v_add_f32_e32 v72, 1.0, v72
	v_add_f32_e32 v73, 1.0, v73
	v_add_f32_e32 v74, 1.0, v74
	v_add_f32_e32 v75, 1.0, v75
	v_add_f32_e32 v76, 1.0, v76
	v_add_f32_e32 v77, 1.0, v77
	v_add_f32_e32 v78, 1.0, v78
	v_add_f32_e32 v79, 1.0, v79
	v_add_f32_e32 v80, 1.0, v80
	v_add_f32_e32 v81, 1.0, v81
	v_rcp_f32_e32 v66, v66
	v_rcp_f32_e32 v67, v67
	v_rcp_f32_e32 v68, v68
	v_rcp_f32_e32 v69, v69
	v_rcp_f32_e32 v70, v70
	v_rcp_f32_e32 v71, v71
	v_rcp_f32_e32 v72, v72
	v_rcp_f32_e32 v73, v73
	v_rcp_f32_e32 v74, v74
	v_rcp_f32_e32 v75, v75
	v_rcp_f32_e32 v76, v76
	v_rcp_f32_e32 v77, v77
	v_rcp_f32_e32 v78, v78
	v_rcp_f32_e32 v79, v79
	v_rcp_f32_e32 v80, v80
	v_rcp_f32_e32 v81, v81
	s_nop 0
.Lroute_ns3:
	v_cvt_pk_bf16_f32 v154, v78, v79
	v_cvt_pk_bf16_f32 v155, v80, v81
	v_cvt_pk_bf16_f32 v156, v74, v75
	v_cvt_pk_bf16_f32 v157, v76, v77
	v_cvt_pk_bf16_f32 v158, v70, v71
	v_cvt_pk_bf16_f32 v159, v72, v73
	v_cvt_pk_bf16_f32 v160, v66, v67
	v_cvt_pk_bf16_f32 v161, v68, v69
	v_lshl_add_u64 v[152:153], s[56:57], 0, v[134:135]
	v_cndmask_b32_dpp v212, v158, v154, vcc quad_perm:[1,0,3,2] row_mask:0xf bank_mask:0xf
	v_cndmask_b32_dpp v213, v159, v155, vcc quad_perm:[1,0,3,2] row_mask:0xf bank_mask:0xf
	v_cndmask_b32_dpp v214, v160, v156, vcc quad_perm:[1,0,3,2] row_mask:0xf bank_mask:0xf
	v_cndmask_b32_dpp v215, v161, v157, vcc quad_perm:[1,0,3,2] row_mask:0xf bank_mask:0xf
	s_not_b64 vcc, vcc
	global_store_dwordx4 v[134:135], v[212:215], off nt
	s_nop 0
	v_cndmask_b32_dpp v216, v154, v158, vcc quad_perm:[1,0,3,2] row_mask:0xf bank_mask:0xf
	v_cndmask_b32_dpp v217, v155, v159, vcc quad_perm:[1,0,3,2] row_mask:0xf bank_mask:0xf
	v_cndmask_b32_dpp v218, v156, v160, vcc quad_perm:[1,0,3,2] row_mask:0xf bank_mask:0xf
	v_cndmask_b32_dpp v219, v157, v161, vcc quad_perm:[1,0,3,2] row_mask:0xf bank_mask:0xf
	s_not_b64 vcc, vcc
	global_store_dwordx4 v[152:153], v[216:219], off nt
	v_lshl_add_u64 v[134:135], s[44:45], 0, v[134:135]
	v_lshl_add_u64 v[134:135], s[44:45], 0, v[134:135]
	v_lshl_add_u64 v[134:135], s[44:45], 0, v[134:135]
	v_lshl_add_u64 v[134:135], s[44:45], 0, v[134:135]
	v_lshl_add_u64 v[134:135], s[44:45], 0, v[134:135]
	s_cmp_lg_u32 s74, 0
	s_cbranch_scc0 .Lroute_ns4
	v_mul_f32_e32 v50, 0xbfb8aa3b, v50
	v_mul_f32_e32 v51, 0xbfb8aa3b, v51
	v_mul_f32_e32 v52, 0xbfb8aa3b, v52
	v_mul_f32_e32 v53, 0xbfb8aa3b, v53
	v_mul_f32_e32 v54, 0xbfb8aa3b, v54
	v_mul_f32_e32 v55, 0xbfb8aa3b, v55
	v_mul_f32_e32 v56, 0xbfb8aa3b, v56
	v_mul_f32_e32 v57, 0xbfb8aa3b, v57
	v_mul_f32_e32 v58, 0xbfb8aa3b, v58
	v_mul_f32_e32 v59, 0xbfb8aa3b, v59
	v_mul_f32_e32 v60, 0xbfb8aa3b, v60
	v_mul_f32_e32 v61, 0xbfb8aa3b, v61
	v_mul_f32_e32 v62, 0xbfb8aa3b, v62
	v_mul_f32_e32 v63, 0xbfb8aa3b, v63
	v_mul_f32_e32 v64, 0xbfb8aa3b, v64
	v_mul_f32_e32 v65, 0xbfb8aa3b, v65
	v_exp_f32_e32 v50, v50
	v_exp_f32_e32 v51, v51
	v_exp_f32_e32 v52, v52
	v_exp_f32_e32 v53, v53
	v_exp_f32_e32 v54, v54
	v_exp_f32_e32 v55, v55
	v_exp_f32_e32 v56, v56
	v_exp_f32_e32 v57, v57
	v_exp_f32_e32 v58, v58
	v_exp_f32_e32 v59, v59
	v_exp_f32_e32 v60, v60
	v_exp_f32_e32 v61, v61
	v_exp_f32_e32 v62, v62
	v_exp_f32_e32 v63, v63
	v_exp_f32_e32 v64, v64
	v_exp_f32_e32 v65, v65
	v_add_f32_e32 v50, 1.0, v50
	v_add_f32_e32 v51, 1.0, v51
	v_add_f32_e32 v52, 1.0, v52
	v_add_f32_e32 v53, 1.0, v53
	v_add_f32_e32 v54, 1.0, v54
	v_add_f32_e32 v55, 1.0, v55
	v_add_f32_e32 v56, 1.0, v56
	v_add_f32_e32 v57, 1.0, v57
	v_add_f32_e32 v58, 1.0, v58
	v_add_f32_e32 v59, 1.0, v59
	v_add_f32_e32 v60, 1.0, v60
	v_add_f32_e32 v61, 1.0, v61
	v_add_f32_e32 v62, 1.0, v62
	v_add_f32_e32 v63, 1.0, v63
	v_add_f32_e32 v64, 1.0, v64
	v_add_f32_e32 v65, 1.0, v65
	v_rcp_f32_e32 v50, v50
	v_rcp_f32_e32 v51, v51
	v_rcp_f32_e32 v52, v52
	v_rcp_f32_e32 v53, v53
	v_rcp_f32_e32 v54, v54
	v_rcp_f32_e32 v55, v55
	v_rcp_f32_e32 v56, v56
	v_rcp_f32_e32 v57, v57
	v_rcp_f32_e32 v58, v58
	v_rcp_f32_e32 v59, v59
	v_rcp_f32_e32 v60, v60
	v_rcp_f32_e32 v61, v61
	v_rcp_f32_e32 v62, v62
	v_rcp_f32_e32 v63, v63
	v_rcp_f32_e32 v64, v64
	v_rcp_f32_e32 v65, v65
	s_nop 0
.Lroute_ns4:
	v_cvt_pk_bf16_f32 v136, v62, v63
	v_cvt_pk_bf16_f32 v137, v64, v65
	v_cvt_pk_bf16_f32 v138, v58, v59
	v_cvt_pk_bf16_f32 v139, v60, v61
	v_cvt_pk_bf16_f32 v140, v54, v55
	v_cvt_pk_bf16_f32 v141, v56, v57
	v_cvt_pk_bf16_f32 v142, v50, v51
	v_cvt_pk_bf16_f32 v143, v52, v53
	v_lshl_add_u64 v[152:153], s[56:57], 0, v[134:135]
	v_cndmask_b32_dpp v144, v140, v136, vcc quad_perm:[1,0,3,2] row_mask:0xf bank_mask:0xf
	v_cndmask_b32_dpp v145, v141, v137, vcc quad_perm:[1,0,3,2] row_mask:0xf bank_mask:0xf
	v_cndmask_b32_dpp v146, v142, v138, vcc quad_perm:[1,0,3,2] row_mask:0xf bank_mask:0xf
	v_cndmask_b32_dpp v147, v143, v139, vcc quad_perm:[1,0,3,2] row_mask:0xf bank_mask:0xf
	s_not_b64 vcc, vcc
	global_store_dwordx4 v[134:135], v[144:147], off nt
	s_nop 0
	v_cndmask_b32_dpp v148, v136, v140, vcc quad_perm:[1,0,3,2] row_mask:0xf bank_mask:0xf
	v_cndmask_b32_dpp v149, v137, v141, vcc quad_perm:[1,0,3,2] row_mask:0xf bank_mask:0xf
	v_cndmask_b32_dpp v150, v138, v142, vcc quad_perm:[1,0,3,2] row_mask:0xf bank_mask:0xf
	v_cndmask_b32_dpp v151, v139, v143, vcc quad_perm:[1,0,3,2] row_mask:0xf bank_mask:0xf
	s_not_b64 vcc, vcc
	global_store_dwordx4 v[152:153], v[148:151], off nt
	v_lshl_add_u64 v[134:135], s[44:45], 0, v[134:135]
	s_cmp_lg_u32 s74, 0
	s_cbranch_scc0 .Lroute_ns5
	v_mul_f32_e32 v34, 0xbfb8aa3b, v34
	v_mul_f32_e32 v35, 0xbfb8aa3b, v35
	v_mul_f32_e32 v36, 0xbfb8aa3b, v36
	v_mul_f32_e32 v37, 0xbfb8aa3b, v37
	v_mul_f32_e32 v38, 0xbfb8aa3b, v38
	v_mul_f32_e32 v39, 0xbfb8aa3b, v39
	v_mul_f32_e32 v40, 0xbfb8aa3b, v40
	v_mul_f32_e32 v41, 0xbfb8aa3b, v41
	v_mul_f32_e32 v42, 0xbfb8aa3b, v42
	v_mul_f32_e32 v43, 0xbfb8aa3b, v43
	v_mul_f32_e32 v44, 0xbfb8aa3b, v44
	v_mul_f32_e32 v45, 0xbfb8aa3b, v45
	v_mul_f32_e32 v46, 0xbfb8aa3b, v46
	v_mul_f32_e32 v47, 0xbfb8aa3b, v47
	v_mul_f32_e32 v48, 0xbfb8aa3b, v48
	v_mul_f32_e32 v49, 0xbfb8aa3b, v49
	v_exp_f32_e32 v34, v34
	v_exp_f32_e32 v35, v35
	v_exp_f32_e32 v36, v36
	v_exp_f32_e32 v37, v37
	v_exp_f32_e32 v38, v38
	v_exp_f32_e32 v39, v39
	v_exp_f32_e32 v40, v40
	v_exp_f32_e32 v41, v41
	v_exp_f32_e32 v42, v42
	v_exp_f32_e32 v43, v43
	v_exp_f32_e32 v44, v44
	v_exp_f32_e32 v45, v45
	v_exp_f32_e32 v46, v46
	v_exp_f32_e32 v47, v47
	v_exp_f32_e32 v48, v48
	v_exp_f32_e32 v49, v49
	v_add_f32_e32 v34, 1.0, v34
	v_add_f32_e32 v35, 1.0, v35
	v_add_f32_e32 v36, 1.0, v36
	v_add_f32_e32 v37, 1.0, v37
	v_add_f32_e32 v38, 1.0, v38
	v_add_f32_e32 v39, 1.0, v39
	v_add_f32_e32 v40, 1.0, v40
	v_add_f32_e32 v41, 1.0, v41
	v_add_f32_e32 v42, 1.0, v42
	v_add_f32_e32 v43, 1.0, v43
	v_add_f32_e32 v44, 1.0, v44
	v_add_f32_e32 v45, 1.0, v45
	v_add_f32_e32 v46, 1.0, v46
	v_add_f32_e32 v47, 1.0, v47
	v_add_f32_e32 v48, 1.0, v48
	v_add_f32_e32 v49, 1.0, v49
	v_rcp_f32_e32 v34, v34
	v_rcp_f32_e32 v35, v35
	v_rcp_f32_e32 v36, v36
	v_rcp_f32_e32 v37, v37
	v_rcp_f32_e32 v38, v38
	v_rcp_f32_e32 v39, v39
	v_rcp_f32_e32 v40, v40
	v_rcp_f32_e32 v41, v41
	v_rcp_f32_e32 v42, v42
	v_rcp_f32_e32 v43, v43
	v_rcp_f32_e32 v44, v44
	v_rcp_f32_e32 v45, v45
	v_rcp_f32_e32 v46, v46
	v_rcp_f32_e32 v47, v47
	v_rcp_f32_e32 v48, v48
	v_rcp_f32_e32 v49, v49
	s_nop 0
.Lroute_ns5:
	v_cvt_pk_bf16_f32 v154, v46, v47
	v_cvt_pk_bf16_f32 v155, v48, v49
	v_cvt_pk_bf16_f32 v156, v42, v43
	v_cvt_pk_bf16_f32 v157, v44, v45
	v_cvt_pk_bf16_f32 v158, v38, v39
	v_cvt_pk_bf16_f32 v159, v40, v41
	v_cvt_pk_bf16_f32 v160, v34, v35
	v_cvt_pk_bf16_f32 v161, v36, v37
	v_lshl_add_u64 v[152:153], s[56:57], 0, v[134:135]
	v_cndmask_b32_dpp v212, v158, v154, vcc quad_perm:[1,0,3,2] row_mask:0xf bank_mask:0xf
	v_cndmask_b32_dpp v213, v159, v155, vcc quad_perm:[1,0,3,2] row_mask:0xf bank_mask:0xf
	v_cndmask_b32_dpp v214, v160, v156, vcc quad_perm:[1,0,3,2] row_mask:0xf bank_mask:0xf
	v_cndmask_b32_dpp v215, v161, v157, vcc quad_perm:[1,0,3,2] row_mask:0xf bank_mask:0xf
	s_not_b64 vcc, vcc
	global_store_dwordx4 v[134:135], v[212:215], off nt
	s_nop 0
	v_cndmask_b32_dpp v216, v154, v158, vcc quad_perm:[1,0,3,2] row_mask:0xf bank_mask:0xf
	v_cndmask_b32_dpp v217, v155, v159, vcc quad_perm:[1,0,3,2] row_mask:0xf bank_mask:0xf
	v_cndmask_b32_dpp v218, v156, v160, vcc quad_perm:[1,0,3,2] row_mask:0xf bank_mask:0xf
	v_cndmask_b32_dpp v219, v157, v161, vcc quad_perm:[1,0,3,2] row_mask:0xf bank_mask:0xf
	s_not_b64 vcc, vcc
	global_store_dwordx4 v[152:153], v[216:219], off nt
	v_lshl_add_u64 v[134:135], s[44:45], 0, v[134:135]
	s_cmp_lg_u32 s74, 0
	s_cbranch_scc0 .Lroute_ns6
	v_mul_f32_e32 v18, 0xbfb8aa3b, v18
	v_mul_f32_e32 v19, 0xbfb8aa3b, v19
	v_mul_f32_e32 v20, 0xbfb8aa3b, v20
	v_mul_f32_e32 v21, 0xbfb8aa3b, v21
	v_mul_f32_e32 v22, 0xbfb8aa3b, v22
	v_mul_f32_e32 v23, 0xbfb8aa3b, v23
	v_mul_f32_e32 v24, 0xbfb8aa3b, v24
	v_mul_f32_e32 v25, 0xbfb8aa3b, v25
	v_mul_f32_e32 v26, 0xbfb8aa3b, v26
	v_mul_f32_e32 v27, 0xbfb8aa3b, v27
	v_mul_f32_e32 v28, 0xbfb8aa3b, v28
	v_mul_f32_e32 v29, 0xbfb8aa3b, v29
	v_mul_f32_e32 v30, 0xbfb8aa3b, v30
	v_mul_f32_e32 v31, 0xbfb8aa3b, v31
	v_mul_f32_e32 v32, 0xbfb8aa3b, v32
	v_mul_f32_e32 v33, 0xbfb8aa3b, v33
	v_exp_f32_e32 v18, v18
	v_exp_f32_e32 v19, v19
	v_exp_f32_e32 v20, v20
	v_exp_f32_e32 v21, v21
	v_exp_f32_e32 v22, v22
	v_exp_f32_e32 v23, v23
	v_exp_f32_e32 v24, v24
	v_exp_f32_e32 v25, v25
	v_exp_f32_e32 v26, v26
	v_exp_f32_e32 v27, v27
	v_exp_f32_e32 v28, v28
	v_exp_f32_e32 v29, v29
	v_exp_f32_e32 v30, v30
	v_exp_f32_e32 v31, v31
	v_exp_f32_e32 v32, v32
	v_exp_f32_e32 v33, v33
	v_add_f32_e32 v18, 1.0, v18
	v_add_f32_e32 v19, 1.0, v19
	v_add_f32_e32 v20, 1.0, v20
	v_add_f32_e32 v21, 1.0, v21
	v_add_f32_e32 v22, 1.0, v22
	v_add_f32_e32 v23, 1.0, v23
	v_add_f32_e32 v24, 1.0, v24
	v_add_f32_e32 v25, 1.0, v25
	v_add_f32_e32 v26, 1.0, v26
	v_add_f32_e32 v27, 1.0, v27
	v_add_f32_e32 v28, 1.0, v28
	v_add_f32_e32 v29, 1.0, v29
	v_add_f32_e32 v30, 1.0, v30
	v_add_f32_e32 v31, 1.0, v31
	v_add_f32_e32 v32, 1.0, v32
	v_add_f32_e32 v33, 1.0, v33
	v_rcp_f32_e32 v18, v18
	v_rcp_f32_e32 v19, v19
	v_rcp_f32_e32 v20, v20
	v_rcp_f32_e32 v21, v21
	v_rcp_f32_e32 v22, v22
	v_rcp_f32_e32 v23, v23
	v_rcp_f32_e32 v24, v24
	v_rcp_f32_e32 v25, v25
	v_rcp_f32_e32 v26, v26
	v_rcp_f32_e32 v27, v27
	v_rcp_f32_e32 v28, v28
	v_rcp_f32_e32 v29, v29
	v_rcp_f32_e32 v30, v30
	v_rcp_f32_e32 v31, v31
	v_rcp_f32_e32 v32, v32
	v_rcp_f32_e32 v33, v33
	s_nop 0
.Lroute_ns6:
	v_cvt_pk_bf16_f32 v136, v30, v31
	v_cvt_pk_bf16_f32 v137, v32, v33
	v_cvt_pk_bf16_f32 v138, v26, v27
	v_cvt_pk_bf16_f32 v139, v28, v29
	v_cvt_pk_bf16_f32 v140, v22, v23
	v_cvt_pk_bf16_f32 v141, v24, v25
	v_cvt_pk_bf16_f32 v142, v18, v19
	v_cvt_pk_bf16_f32 v143, v20, v21
	v_lshl_add_u64 v[152:153], s[56:57], 0, v[134:135]
	v_cndmask_b32_dpp v144, v140, v136, vcc quad_perm:[1,0,3,2] row_mask:0xf bank_mask:0xf
	v_cndmask_b32_dpp v145, v141, v137, vcc quad_perm:[1,0,3,2] row_mask:0xf bank_mask:0xf
	v_cndmask_b32_dpp v146, v142, v138, vcc quad_perm:[1,0,3,2] row_mask:0xf bank_mask:0xf
	v_cndmask_b32_dpp v147, v143, v139, vcc quad_perm:[1,0,3,2] row_mask:0xf bank_mask:0xf
	s_not_b64 vcc, vcc
	global_store_dwordx4 v[134:135], v[144:147], off nt
	s_nop 0
	v_cndmask_b32_dpp v148, v136, v140, vcc quad_perm:[1,0,3,2] row_mask:0xf bank_mask:0xf
	v_cndmask_b32_dpp v149, v137, v141, vcc quad_perm:[1,0,3,2] row_mask:0xf bank_mask:0xf
	v_cndmask_b32_dpp v150, v138, v142, vcc quad_perm:[1,0,3,2] row_mask:0xf bank_mask:0xf
	v_cndmask_b32_dpp v151, v139, v143, vcc quad_perm:[1,0,3,2] row_mask:0xf bank_mask:0xf
	s_not_b64 vcc, vcc
	global_store_dwordx4 v[152:153], v[148:151], off nt
	v_lshl_add_u64 v[134:135], s[44:45], 0, v[134:135]
	s_cmp_lg_u32 s74, 0
	s_cbranch_scc0 .Lroute_ns7
	v_mul_f32_e32 v2, 0xbfb8aa3b, v2
	v_mul_f32_e32 v3, 0xbfb8aa3b, v3
	v_mul_f32_e32 v4, 0xbfb8aa3b, v4
	v_mul_f32_e32 v5, 0xbfb8aa3b, v5
	v_mul_f32_e32 v6, 0xbfb8aa3b, v6
	v_mul_f32_e32 v7, 0xbfb8aa3b, v7
	v_mul_f32_e32 v8, 0xbfb8aa3b, v8
	v_mul_f32_e32 v9, 0xbfb8aa3b, v9
	v_mul_f32_e32 v10, 0xbfb8aa3b, v10
	v_mul_f32_e32 v11, 0xbfb8aa3b, v11
	v_mul_f32_e32 v12, 0xbfb8aa3b, v12
	v_mul_f32_e32 v13, 0xbfb8aa3b, v13
	v_mul_f32_e32 v14, 0xbfb8aa3b, v14
	v_mul_f32_e32 v15, 0xbfb8aa3b, v15
	v_mul_f32_e32 v16, 0xbfb8aa3b, v16
	v_mul_f32_e32 v17, 0xbfb8aa3b, v17
	v_exp_f32_e32 v2, v2
	v_exp_f32_e32 v3, v3
	v_exp_f32_e32 v4, v4
	v_exp_f32_e32 v5, v5
	v_exp_f32_e32 v6, v6
	v_exp_f32_e32 v7, v7
	v_exp_f32_e32 v8, v8
	v_exp_f32_e32 v9, v9
	v_exp_f32_e32 v10, v10
	v_exp_f32_e32 v11, v11
	v_exp_f32_e32 v12, v12
	v_exp_f32_e32 v13, v13
	v_exp_f32_e32 v14, v14
	v_exp_f32_e32 v15, v15
	v_exp_f32_e32 v16, v16
	v_exp_f32_e32 v17, v17
	v_add_f32_e32 v2, 1.0, v2
	v_add_f32_e32 v3, 1.0, v3
	v_add_f32_e32 v4, 1.0, v4
	v_add_f32_e32 v5, 1.0, v5
	v_add_f32_e32 v6, 1.0, v6
	v_add_f32_e32 v7, 1.0, v7
	v_add_f32_e32 v8, 1.0, v8
	v_add_f32_e32 v9, 1.0, v9
	v_add_f32_e32 v10, 1.0, v10
	v_add_f32_e32 v11, 1.0, v11
	v_add_f32_e32 v12, 1.0, v12
	v_add_f32_e32 v13, 1.0, v13
	v_add_f32_e32 v14, 1.0, v14
	v_add_f32_e32 v15, 1.0, v15
	v_add_f32_e32 v16, 1.0, v16
	v_add_f32_e32 v17, 1.0, v17
	v_rcp_f32_e32 v2, v2
	v_rcp_f32_e32 v3, v3
	v_rcp_f32_e32 v4, v4
	v_rcp_f32_e32 v5, v5
	v_rcp_f32_e32 v6, v6
	v_rcp_f32_e32 v7, v7
	v_rcp_f32_e32 v8, v8
	v_rcp_f32_e32 v9, v9
	v_rcp_f32_e32 v10, v10
	v_rcp_f32_e32 v11, v11
	v_rcp_f32_e32 v12, v12
	v_rcp_f32_e32 v13, v13
	v_rcp_f32_e32 v14, v14
	v_rcp_f32_e32 v15, v15
	v_rcp_f32_e32 v16, v16
	v_rcp_f32_e32 v17, v17
	s_nop 0
.Lroute_ns7:
	v_cvt_pk_bf16_f32 v154, v14, v15
	v_cvt_pk_bf16_f32 v155, v16, v17
	v_cvt_pk_bf16_f32 v156, v10, v11
	v_cvt_pk_bf16_f32 v157, v12, v13
	v_cvt_pk_bf16_f32 v158, v6, v7
	v_cvt_pk_bf16_f32 v159, v8, v9
	v_cvt_pk_bf16_f32 v160, v2, v3
	v_cvt_pk_bf16_f32 v161, v4, v5
	v_lshl_add_u64 v[152:153], s[56:57], 0, v[134:135]
	v_cndmask_b32_dpp v212, v158, v154, vcc quad_perm:[1,0,3,2] row_mask:0xf bank_mask:0xf
	v_cndmask_b32_dpp v213, v159, v155, vcc quad_perm:[1,0,3,2] row_mask:0xf bank_mask:0xf
	v_cndmask_b32_dpp v214, v160, v156, vcc quad_perm:[1,0,3,2] row_mask:0xf bank_mask:0xf
	v_cndmask_b32_dpp v215, v161, v157, vcc quad_perm:[1,0,3,2] row_mask:0xf bank_mask:0xf
	s_not_b64 vcc, vcc
	global_store_dwordx4 v[134:135], v[212:215], off nt
	s_nop 0
	v_cndmask_b32_dpp v216, v154, v158, vcc quad_perm:[1,0,3,2] row_mask:0xf bank_mask:0xf
	v_cndmask_b32_dpp v217, v155, v159, vcc quad_perm:[1,0,3,2] row_mask:0xf bank_mask:0xf
	v_cndmask_b32_dpp v218, v156, v160, vcc quad_perm:[1,0,3,2] row_mask:0xf bank_mask:0xf
	v_cndmask_b32_dpp v219, v157, v161, vcc quad_perm:[1,0,3,2] row_mask:0xf bank_mask:0xf
	s_not_b64 vcc, vcc
	global_store_dwordx4 v[152:153], v[216:219], off nt

	.amdhsa_kernel _Z6mk_fwd6Params
		.amdhsa_group_segment_fixed_size 0
		.amdhsa_private_segment_fixed_size 0
		.amdhsa_kernarg_size 552
		.amdhsa_user_sgpr_count 2
		.amdhsa_user_sgpr_dispatch_ptr 0
		.amdhsa_user_sgpr_queue_ptr 0
		.amdhsa_user_sgpr_kernarg_segment_ptr 1
		.amdhsa_user_sgpr_dispatch_id 0
		.amdhsa_user_sgpr_kernarg_preload_length 0
		.amdhsa_user_sgpr_kernarg_preload_offset 0
		.amdhsa_user_sgpr_private_segment_size 0
		.amdhsa_uses_dynamic_stack 0
		.amdhsa_enable_private_segment 0
		.amdhsa_system_sgpr_workgroup_id_x 1
		.amdhsa_system_sgpr_workgroup_id_y 0
		.amdhsa_system_sgpr_workgroup_id_z 0
		.amdhsa_system_sgpr_workgroup_info 0
		.amdhsa_system_vgpr_workitem_id 2
		.amdhsa_next_free_vgpr 256
		.amdhsa_next_free_sgpr 102
		.amdhsa_accum_offset 256
		.amdhsa_reserve_vcc 1
		.amdhsa_float_round_mode_32 0
		.amdhsa_float_round_mode_16_64 0
		.amdhsa_float_denorm_mode_32 3
		.amdhsa_float_denorm_mode_16_64 3
		.amdhsa_dx10_clamp 1
		.amdhsa_ieee_mode 1
		.amdhsa_fp16_overflow 0
		.amdhsa_tg_split 0
		.amdhsa_exception_fp_ieee_invalid_op 0
		.amdhsa_exception_fp_denorm_src 0
		.amdhsa_exception_fp_ieee_div_zero 0
		.amdhsa_exception_fp_ieee_overflow 0
		.amdhsa_exception_fp_ieee_underflow 0
		.amdhsa_exception_fp_ieee_inexact 0
		.amdhsa_exception_int_div_zero 0
	.end_amdhsa_kernel

amdhsa.kernels:
  - .agpr_count:     0
    .args:
      - .offset:         0
        .size:           296
        .value_kind:     by_value
      - .offset:         296
        .size:           4
        .value_kind:     hidden_block_count_x
      - .offset:         300
        .size:           4
        .value_kind:     hidden_block_count_y
      - .offset:         304
        .size:           4
        .value_kind:     hidden_block_count_z
      - .offset:         308
        .size:           2
        .value_kind:     hidden_group_size_x
      - .offset:         310
        .size:           2
        .value_kind:     hidden_group_size_y
      - .offset:         312
        .size:           2
        .value_kind:     hidden_group_size_z
      - .offset:         314
        .size:           2
        .value_kind:     hidden_remainder_x
      - .offset:         316
        .size:           2
        .value_kind:     hidden_remainder_y
      - .offset:         318
        .size:           2
        .value_kind:     hidden_remainder_z
      - .offset:         336
        .size:           8
        .value_kind:     hidden_global_offset_x
      - .offset:         344
        .size:           8
        .value_kind:     hidden_global_offset_y
      - .offset:         352
        .size:           8
        .value_kind:     hidden_global_offset_z
      - .offset:         360
        .size:           2
        .value_kind:     hidden_grid_dims
      - .offset:         384
        .size:           8
        .value_kind:     hidden_multigrid_sync_arg
      - .offset:         416
        .size:           4
        .value_kind:     hidden_dynamic_lds_size
    .group_segment_fixed_size: 0
    .kernarg_segment_align: 8
    .kernarg_segment_size: 552
    .language:       OpenCL C
    .language_version:
      - 2
      - 0
    .max_flat_workgroup_size: 512
    .name:           _Z6mk_fwd6Params
    .private_segment_fixed_size: 0
    .sgpr_count:     108
    .sgpr_spill_count: 85
    .symbol:         _Z6mk_fwd6Params.kd
    .uniform_work_group_size: 1
    .uses_dynamic_stack: false
    .vgpr_count:     256
    .vgpr_spill_count: 0
    .wavefront_size: 64
